# GEMM1 phase entry: per-XCC staggered start (0..7 x 0.8us) to break first-round K-lockstep
# baseline (speedup 1.0000x reference)
.LBB0_303:
	s_or_b64 exec, exec, s[0:1]
	v_readlane_b32 s2, v254, 5
	v_mov_b32_e32 v2, v220
	v_readlane_b32 s3, v254, 6
	s_waitcnt lgkmcnt(0)
	s_barrier
	s_and_b64 vcc, exec, s[2:3]
	v_readfirstlane_b32 s0, v2
	s_cbranch_vccz .LBB0_364
	v_readlane_b32 s100, v252, 8
	s_nop 0
	s_lshr_b32 s100, s100, 3
	s_and_b32 s100, s100, 7
.Lstg_loop:
	s_cmp_eq_u32 s100, 0
	s_cbranch_scc1 .Lstg_done
	s_sleep 30
	s_sub_u32 s100, s100, 1
	s_branch .Lstg_loop
.Lstg_done:
	v_lshlrev_b32_e32 v1, 4, v2
	v_add_u32_e32 v4, 0x2000, v1
	v_ashrrev_i32_e32 v3, 31, v4
	v_lshrrev_b32_e32 v3, 22, v3
	v_add_u32_e32 v3, v4, v3
	v_ashrrev_i32_e32 v3, 10, v3
	v_mul_i32_i24_e32 v5, 0x400, v3
	v_sub_u32_e32 v4, v4, v5
	v_lshrrev_b32_e32 v5, 4, v4
	v_bitop3_b32 v5, v5, v4, 32 bitop3:0x6c
	v_ashrrev_i32_e32 v4, 31, v5
	v_lshrrev_b32_e32 v4, 26, v4
	v_add_u32_e32 v6, v5, v4
	v_lshlrev_b32_e32 v7, 3, v3
	s_mul_i32 s34, s97, 0x1a00000
	v_ashrrev_i32_e32 v4, 6, v6
	v_and_b32_e32 v7, -16, v7
	s_lshl_b64 s[2:3], s[34:35], 1
	v_readlane_b32 s4, v253, 8
	v_add_u32_e32 v7, v4, v7
	s_add_u32 s8, s4, s2
	v_and_b32_e32 v8, 3, v4
	s_mov_b32 s2, 0xfffe0
	v_lshrrev_b32_e32 v9, 2, v7
	v_lshlrev_b32_e32 v10, 1, v7
	v_and_b32_e32 v6, 0xc0, v6
	v_and_or_b32 v8, v7, s2, v8
	v_and_b32_e32 v9, 4, v9
	v_and_b32_e32 v10, 24, v10
	v_sub_u32_e32 v5, v5, v6
	v_or3_b32 v8, v8, v9, v10
	v_lshlrev_b32_e32 v9, 5, v3
	v_ashrrev_i16_sdwa v5, v223, sext(v5) dst_sel:DWORD dst_unused:UNUSED_PAD src0_sel:DWORD src1_sel:BYTE_0
	v_and_b32_e32 v9, 32, v9
	v_bfe_i32 v5, v5, 0, 16
	v_add_lshl_u32 v6, v9, v5, 1
	v_lshl_add_u32 v130, v8, 12, v6
	v_lshl_add_u32 v132, v7, 12, v6
	v_bfe_i32 v6, v2, 27, 1
	v_lshrrev_b32_e32 v6, 22, v6
	v_add_u32_e32 v6, v1, v6
	v_and_b32_e32 v6, 0xfffffc00, v6
	v_sub_u32_e32 v1, v1, v6
	v_lshrrev_b32_e32 v6, 4, v1
	v_ashrrev_i32_e32 v7, 31, v2
	v_bitop3_b32 v1, v6, v1, 32 bitop3:0x6c
	v_lshrrev_b32_e32 v7, 26, v7
	v_ashrrev_i32_e32 v6, 31, v1
	v_add_u32_e32 v7, v2, v7
	v_lshrrev_b32_e32 v6, 26, v6
	v_ashrrev_i32_e32 v7, 6, v7
	v_add_u32_e32 v8, v1, v6
	v_lshlrev_b32_e32 v9, 3, v7
	v_ashrrev_i32_e32 v6, 6, v8
	v_and_b32_e32 v9, -16, v9
	v_add_u32_e32 v9, v6, v9
	v_readlane_b32 s5, v253, 9
	v_and_b32_e32 v10, 3, v6
	v_lshrrev_b32_e32 v11, 2, v9
	v_lshlrev_b32_e32 v12, 1, v9
	v_and_b32_e32 v8, 0xc0, v8
	s_addc_u32 s9, s5, s3
	s_ashr_i32 s1, s0, 6
	v_and_or_b32 v10, v9, s2, v10
	v_and_b32_e32 v11, 4, v11
	v_and_b32_e32 v12, 24, v12
	v_sub_u32_e32 v1, v1, v8
	s_ashr_i32 s10, s0, 8
	s_lshl_b32 s19, s1, 10
	v_or3_b32 v10, v10, v11, v12
	v_lshlrev_b32_e32 v11, 5, v7
	v_ashrrev_i16_sdwa v1, v223, sext(v1) dst_sel:DWORD dst_unused:UNUSED_PAD src0_sel:DWORD src1_sel:BYTE_0
	v_readlane_b32 s2, v254, 46
	v_and_b32_e32 v11, 32, v11
	v_bfe_i32 v8, v1, 0, 16
	v_readlane_b32 s3, v254, 47
	s_add_u32 s4, s8, s2
	v_add_lshl_u32 v1, v11, v8, 1
	s_addc_u32 s5, s9, s3
	s_add_i32 s22, s19, 0
	v_lshl_add_u32 v134, v10, 12, v1
	s_add_i32 m0, s22, 0x10000
	v_lshl_add_u32 v136, v9, 12, v1
	global_load_lds_dwordx4 v134, s[4:5]
	s_add_i32 m0, s22, 0x12000
	s_add_u32 s2, s4, 0x80000
	global_load_lds_dwordx4 v130, s[4:5]
	s_addc_u32 s3, s5, 0
	s_add_i32 m0, s22, 0x14000
	s_add_i32 s23, s22, 0x2000
	global_load_lds_dwordx4 v134, s[2:3]
	s_add_i32 m0, s22, 0x16000
	s_add_i32 s24, s22, 0x4000
	global_load_lds_dwordx4 v130, s[2:3]
	v_readlane_b32 s2, v254, 53
	s_mov_b32 m0, s22
	v_readlane_b32 s3, v254, 54
	s_add_i32 s25, s22, 0x6000
	s_cmp_eq_u32 s10, 1
	s_nop 2
	global_load_lds_dwordx4 v136, s[2:3]
	s_mov_b32 m0, s23
	s_nop 0
	global_load_lds_dwordx4 v132, s[2:3]
	v_readlane_b32 s2, v254, 55
	s_mov_b32 m0, s24
	v_readlane_b32 s3, v254, 56
	s_nop 4
	global_load_lds_dwordx4 v136, s[2:3]
	s_mov_b32 m0, s25
	s_nop 0
	global_load_lds_dwordx4 v132, s[2:3]
	s_cselect_b64 s[2:3], -1, 0
	s_cmp_lg_u32 s10, 1
	s_cbranch_scc1 .LBB0_306
	s_barrier
